# mixer phase work queue: pool/conv units interleaved with attention units (even index attention, odd index pool/conv) instead of all attention first, so memory-latency-bound and VALU-bound units overla
# speedup vs baseline: 1.0130x; 1.0130x over previous
.LBB0_1104:
	s_add_i32 s94, 0, 0x20140
	s_mov_b64 s[4:5], src_shared_base
	s_cmp_lg_u32 s94, -1
	s_cselect_b32 s4, s94, 0
	s_cselect_b32 s5, s5, 0
	v_mov_b32_e32 v2, s4
	v_mov_b32_e32 v3, s5
	s_waitcnt vmcnt(0) lgkmcnt(0)
	s_barrier
	flat_load_dword v0, v[2:3] sc0 sc1
	s_waitcnt vmcnt(0)
	s_mov_b64 s[38:39], -1
	s_waitcnt lgkmcnt(0)
	v_readfirstlane_b32 s95, v0
	s_cmpk_gt_i32 s95, 0x847
	s_cbranch_scc1 .LBB0_1103
	s_cmpk_lt_i32 s95, 0x810
	s_cbranch_scc0 .Lmix_rm_hi
	s_lshr_b32 s4, s95, 1
	s_bitcmp1_b32 s95, 0
	s_cselect_b32 s5, 0x440, 0
	s_add_i32 s95, s4, s5
	s_branch .Lmix_rm_done
.Lmix_rm_hi:
	s_addk_i32 s95, 0xfbf8
.Lmix_rm_done:
	v_mov_b32_e32 v197, 0
	s_mov_b64 s[38:39], exec
	v_readlane_b32 s4, v253, 0
	v_readlane_b32 s5, v253, 1
	s_and_b64 s[4:5], s[38:39], s[4:5]
	s_mov_b64 exec, s[4:5]
	s_cbranch_execz .LBB0_1109
	s_mov_b64 s[42:43], exec
	v_mbcnt_lo_u32_b32 v0, s42, 0
	v_mbcnt_hi_u32_b32 v0, s43, v0
	v_cmp_eq_u32_e32 vcc, 0, v0
	s_and_saveexec_b64 s[40:41], vcc
	s_cbranch_execz .LBB0_1108
	s_bcnt1_i32_b64 s4, s[42:43]
	v_mov_b32_e32 v2, s4
	v_readlane_b32 s4, v255, 21
	v_readlane_b32 s5, v255, 22
	s_nop 4
	global_atomic_add v2, v1, v2, s[4:5] offset:256 sc0
